# c6 + in-proj epilogue bias loads issued together behind one wait
# baseline (speedup 1.0000x reference)
.LBB0_409:
	s_add_u32 s8, s84, 0xfffc0080
	s_addc_u32 s9, s85, -1
	s_add_i32 s10, 0, 0x10000
	v_add_u32_e32 v0, s10, v159
	ds_read_b128 v[142:145], v0
	ds_read_b128 v[146:149], v0 offset:1024
	ds_read_b128 v[150:153], v0 offset:2048
	ds_read_b128 v[154:157], v0 offset:3072
	s_cmp_eq_u32 s46, 12
	s_cselect_b32 s89, s23, s9
	s_cselect_b32 s88, s60, s8
	s_cselect_b32 s87, s21, vcc_hi
	s_cselect_b32 s86, s61, vcc_lo
	v_lshl_add_u64 v[196:197], s[84:85], 0, v[140:141]
	s_add_i32 m0, s25, 0xc000
	ds_read_b128 v[180:183], v177
	ds_read_b128 v[184:187], v177 offset:1024
	ds_read_b128 v[188:191], v177 offset:2048
	ds_read_b128 v[192:195], v177 offset:3072
	ds_read_b128 v[200:203], v177 offset:4096
	ds_read_b128 v[204:207], v177 offset:5120
	ds_read_b128 v[208:211], v177 offset:6144
	ds_read_b128 v[212:215], v177 offset:7168
	global_load_lds_dwordx4 v[196:197], off
	v_lshl_add_u64 v[196:197], s[84:85], 0, v[138:139]
	s_add_i32 m0, s25, 0xe000
	s_nop 0
	global_load_lds_dwordx4 v[196:197], off
	s_waitcnt lgkmcnt(8)
	s_barrier
	s_waitcnt lgkmcnt(0)
	s_setprio 1
	s_waitcnt lgkmcnt(0)
	v_mfma_f32_16x16x32_bf16 v[126:129], v[142:145], v[180:183], v[126:129]
	v_mfma_f32_16x16x32_bf16 v[118:121], v[150:153], v[180:183], v[118:121]
	v_mfma_f32_16x16x32_bf16 v[122:125], v[142:145], v[188:191], v[122:125]
	v_mfma_f32_16x16x32_bf16 v[110:113], v[150:153], v[188:191], v[110:113]
	v_mfma_f32_16x16x32_bf16 v[114:117], v[142:145], v[200:203], v[114:117]
	v_mfma_f32_16x16x32_bf16 v[102:105], v[150:153], v[200:203], v[102:105]
	v_mfma_f32_16x16x32_bf16 v[106:109], v[142:145], v[208:211], v[106:109]
	v_mfma_f32_16x16x32_bf16 v[98:101], v[150:153], v[208:211], v[98:101]
	v_mfma_f32_16x16x32_bf16 v[126:129], v[146:149], v[184:187], v[126:129]
	v_mfma_f32_16x16x32_bf16 v[118:121], v[154:157], v[184:187], v[118:121]
	v_mfma_f32_16x16x32_bf16 v[122:125], v[146:149], v[192:195], v[122:125]
	v_mfma_f32_16x16x32_bf16 v[110:113], v[154:157], v[192:195], v[110:113]
	v_mfma_f32_16x16x32_bf16 v[114:117], v[146:149], v[204:207], v[114:117]
	v_mfma_f32_16x16x32_bf16 v[102:105], v[154:157], v[204:207], v[102:105]
	v_mfma_f32_16x16x32_bf16 v[106:109], v[146:149], v[212:215], v[106:109]
	v_mfma_f32_16x16x32_bf16 v[98:101], v[154:157], v[212:215], v[98:101]
	s_setprio 0
	s_barrier
	s_add_i32 s11, 0, 0x14000
	s_add_i32 s8, s10, s59
	v_add_u32_e32 v0, s11, v159
	v_lshl_add_u64 v[196:197], s[86:87], 0, v[132:133]
	s_mov_b32 m0, s8
	ds_read_b128 v[218:221], v0
	ds_read_b128 v[222:225], v0 offset:1024
	ds_read_b128 v[226:229], v0 offset:2048
	ds_read_b128 v[230:233], v0 offset:3072
	global_load_lds_dwordx4 v[196:197], off
	v_lshl_add_u64 v[198:199], s[86:87], 0, v[136:137]
	s_add_i32 m0, s8, 0x2000
	s_nop 0
	global_load_lds_dwordx4 v[198:199], off
	s_barrier
	s_waitcnt lgkmcnt(0)
	s_setprio 1
	s_waitcnt lgkmcnt(0)
	v_mfma_f32_16x16x32_bf16 v[62:65], v[218:221], v[180:183], v[62:65]
	v_mfma_f32_16x16x32_bf16 v[54:57], v[226:229], v[180:183], v[54:57]
	v_mfma_f32_16x16x32_bf16 v[58:61], v[218:221], v[188:191], v[58:61]
	v_mfma_f32_16x16x32_bf16 v[46:49], v[226:229], v[188:191], v[46:49]
	v_mfma_f32_16x16x32_bf16 v[50:53], v[218:221], v[200:203], v[50:53]
	v_mfma_f32_16x16x32_bf16 v[38:41], v[226:229], v[200:203], v[38:41]
	v_mfma_f32_16x16x32_bf16 v[42:45], v[218:221], v[208:211], v[42:45]
	v_mfma_f32_16x16x32_bf16 v[34:37], v[226:229], v[208:211], v[34:37]
	v_mfma_f32_16x16x32_bf16 v[62:65], v[222:225], v[184:187], v[62:65]
	v_mfma_f32_16x16x32_bf16 v[54:57], v[230:233], v[184:187], v[54:57]
	v_mfma_f32_16x16x32_bf16 v[58:61], v[222:225], v[192:195], v[58:61]
	v_mfma_f32_16x16x32_bf16 v[46:49], v[230:233], v[192:195], v[46:49]
	v_mfma_f32_16x16x32_bf16 v[50:53], v[222:225], v[204:207], v[50:53]
	v_mfma_f32_16x16x32_bf16 v[38:41], v[230:233], v[204:207], v[38:41]
	v_mfma_f32_16x16x32_bf16 v[42:45], v[222:225], v[212:215], v[42:45]
	v_mfma_f32_16x16x32_bf16 v[34:37], v[230:233], v[212:215], v[34:37]
	s_setprio 0
	s_mov_b32 m0, s25
	v_lshl_add_u64 v[234:235], s[88:89], 0, v[130:131]
	s_barrier
	ds_read_b128 v[180:183], v177 offset:16384
	ds_read_b128 v[184:187], v177 offset:17408
	ds_read_b128 v[188:191], v177 offset:18432
	ds_read_b128 v[192:195], v177 offset:19456
	ds_read_b128 v[200:203], v177 offset:20480
	ds_read_b128 v[204:207], v177 offset:21504
	ds_read_b128 v[208:211], v177 offset:22528
	ds_read_b128 v[212:215], v177 offset:23552
	global_load_lds_dwordx4 v[234:235], off
	v_lshl_add_u64 v[236:237], s[88:89], 0, v[134:135]
	s_mov_b32 m0, s76
	s_nop 0
	global_load_lds_dwordx4 v[236:237], off
	s_barrier
	s_waitcnt lgkmcnt(0)
	s_setprio 1
	s_waitcnt lgkmcnt(0)
	v_mfma_f32_16x16x32_bf16 v[94:97], v[142:145], v[180:183], v[94:97]
	v_mfma_f32_16x16x32_bf16 v[86:89], v[150:153], v[180:183], v[86:89]
	v_mfma_f32_16x16x32_bf16 v[90:93], v[142:145], v[188:191], v[90:93]
	v_mfma_f32_16x16x32_bf16 v[78:81], v[150:153], v[188:191], v[78:81]
	v_mfma_f32_16x16x32_bf16 v[82:85], v[142:145], v[200:203], v[82:85]
	v_mfma_f32_16x16x32_bf16 v[70:73], v[150:153], v[200:203], v[70:73]
	v_mfma_f32_16x16x32_bf16 v[74:77], v[142:145], v[208:211], v[74:77]
	v_mfma_f32_16x16x32_bf16 v[66:69], v[150:153], v[208:211], v[66:69]
	v_mfma_f32_16x16x32_bf16 v[94:97], v[146:149], v[184:187], v[94:97]
	v_mfma_f32_16x16x32_bf16 v[86:89], v[154:157], v[184:187], v[86:89]
	v_mfma_f32_16x16x32_bf16 v[90:93], v[146:149], v[192:195], v[90:93]
	v_mfma_f32_16x16x32_bf16 v[78:81], v[154:157], v[192:195], v[78:81]
	v_mfma_f32_16x16x32_bf16 v[82:85], v[146:149], v[204:207], v[82:85]
	v_mfma_f32_16x16x32_bf16 v[70:73], v[154:157], v[204:207], v[70:73]
	v_mfma_f32_16x16x32_bf16 v[74:77], v[146:149], v[212:215], v[74:77]
	v_mfma_f32_16x16x32_bf16 v[66:69], v[154:157], v[212:215], v[66:69]
	s_setprio 0
	s_barrier
	s_add_u32 s8, s86, 0x40000
	s_addc_u32 s9, s87, 0
	s_add_i32 s10, s11, s59
	v_lshl_add_u64 v[142:143], s[8:9], 0, v[132:133]
	s_mov_b32 m0, s10
	s_nop 0
	global_load_lds_dwordx4 v[142:143], off
	v_lshl_add_u64 v[142:143], s[8:9], 0, v[136:137]
	s_add_i32 m0, s10, 0x2000
	s_nop 0
	global_load_lds_dwordx4 v[142:143], off
	s_waitcnt vmcnt(6)
	s_barrier
	s_setprio 1
	v_mfma_f32_16x16x32_bf16 v[30:33], v[218:221], v[180:183], v[30:33]
	v_mfma_f32_16x16x32_bf16 v[22:25], v[226:229], v[180:183], v[22:25]
	v_mfma_f32_16x16x32_bf16 v[26:29], v[218:221], v[188:191], v[26:29]
	v_mfma_f32_16x16x32_bf16 v[14:17], v[226:229], v[188:191], v[14:17]
	v_mfma_f32_16x16x32_bf16 v[18:21], v[218:221], v[200:203], v[18:21]
	v_mfma_f32_16x16x32_bf16 v[6:9], v[226:229], v[200:203], v[6:9]
	v_mfma_f32_16x16x32_bf16 v[10:13], v[218:221], v[208:211], v[10:13]
	v_mfma_f32_16x16x32_bf16 v[2:5], v[226:229], v[208:211], v[2:5]
	v_mfma_f32_16x16x32_bf16 v[30:33], v[222:225], v[184:187], v[30:33]
	v_mfma_f32_16x16x32_bf16 v[22:25], v[230:233], v[184:187], v[22:25]
	v_mfma_f32_16x16x32_bf16 v[26:29], v[222:225], v[192:195], v[26:29]
	v_mfma_f32_16x16x32_bf16 v[14:17], v[230:233], v[192:195], v[14:17]
	v_mfma_f32_16x16x32_bf16 v[18:21], v[222:225], v[204:207], v[18:21]
	v_mfma_f32_16x16x32_bf16 v[6:9], v[230:233], v[204:207], v[6:9]
	v_mfma_f32_16x16x32_bf16 v[10:13], v[222:225], v[212:215], v[10:13]
	v_mfma_f32_16x16x32_bf16 v[2:5], v[230:233], v[212:215], v[2:5]
	s_setprio 0
	s_add_i32 s10, 0, 0x18000
	v_add_u32_e32 v0, s10, v159
	s_barrier
	ds_read_b128 v[142:145], v0
	ds_read_b128 v[146:149], v0 offset:1024
	ds_read_b128 v[150:153], v0 offset:2048
	ds_read_b128 v[154:157], v0 offset:3072
	s_add_u32 s8, s88, 0x40000
	s_addc_u32 s9, s89, 0
	s_mov_b32 m0, s79
	v_lshl_add_u64 v[218:219], s[8:9], 0, v[130:131]
	ds_read_b128 v[180:183], v177 offset:32768
	ds_read_b128 v[184:187], v177 offset:33792
	ds_read_b128 v[188:191], v177 offset:34816
	ds_read_b128 v[192:195], v177 offset:35840
	ds_read_b128 v[200:203], v177 offset:36864
	ds_read_b128 v[204:207], v177 offset:37888
	ds_read_b128 v[208:211], v177 offset:38912
	ds_read_b128 v[212:215], v177 offset:39936
	global_load_lds_dwordx4 v[218:219], off
	v_lshl_add_u64 v[218:219], s[8:9], 0, v[134:135]
	s_mov_b32 m0, s93
	s_nop 0
	global_load_lds_dwordx4 v[218:219], off
	s_waitcnt lgkmcnt(8)
	s_barrier
	s_waitcnt lgkmcnt(0)
	s_setprio 1
	s_waitcnt lgkmcnt(0)
	v_mfma_f32_16x16x32_bf16 v[126:129], v[142:145], v[180:183], v[126:129]
	v_mfma_f32_16x16x32_bf16 v[118:121], v[150:153], v[180:183], v[118:121]
	v_mfma_f32_16x16x32_bf16 v[122:125], v[142:145], v[188:191], v[122:125]
	v_mfma_f32_16x16x32_bf16 v[110:113], v[150:153], v[188:191], v[110:113]
	v_mfma_f32_16x16x32_bf16 v[114:117], v[142:145], v[200:203], v[114:117]
	v_mfma_f32_16x16x32_bf16 v[102:105], v[150:153], v[200:203], v[102:105]
	v_mfma_f32_16x16x32_bf16 v[106:109], v[142:145], v[208:211], v[106:109]
	v_mfma_f32_16x16x32_bf16 v[98:101], v[150:153], v[208:211], v[98:101]
	v_mfma_f32_16x16x32_bf16 v[126:129], v[146:149], v[184:187], v[126:129]
	v_mfma_f32_16x16x32_bf16 v[118:121], v[154:157], v[184:187], v[118:121]
	v_mfma_f32_16x16x32_bf16 v[122:125], v[146:149], v[192:195], v[122:125]
	v_mfma_f32_16x16x32_bf16 v[110:113], v[154:157], v[192:195], v[110:113]
	v_mfma_f32_16x16x32_bf16 v[114:117], v[146:149], v[204:207], v[114:117]
	v_mfma_f32_16x16x32_bf16 v[102:105], v[154:157], v[204:207], v[102:105]
	v_mfma_f32_16x16x32_bf16 v[106:109], v[146:149], v[212:215], v[106:109]
	v_mfma_f32_16x16x32_bf16 v[98:101], v[154:157], v[212:215], v[98:101]
	s_setprio 0
	s_barrier
	s_add_i32 s11, 0, 0x1c000
	s_add_i32 s8, s10, s59
	v_add_u32_e32 v0, s11, v159
	v_lshl_add_u64 v[196:197], v[196:197], 0, s[48:49]
	s_mov_b32 m0, s8
	ds_read_b128 v[218:221], v0
	ds_read_b128 v[222:225], v0 offset:1024
	ds_read_b128 v[226:229], v0 offset:2048
	ds_read_b128 v[230:233], v0 offset:3072
	global_load_lds_dwordx4 v[196:197], off
	v_lshl_add_u64 v[196:197], v[198:199], 0, s[48:49]
	s_add_i32 m0, s8, 0x2000
	s_nop 0
	global_load_lds_dwordx4 v[196:197], off
	s_barrier
	s_waitcnt lgkmcnt(0)
	s_setprio 1
	s_waitcnt lgkmcnt(0)
	v_mfma_f32_16x16x32_bf16 v[62:65], v[218:221], v[180:183], v[62:65]
	v_mfma_f32_16x16x32_bf16 v[54:57], v[226:229], v[180:183], v[54:57]
	v_mfma_f32_16x16x32_bf16 v[58:61], v[218:221], v[188:191], v[58:61]
	v_mfma_f32_16x16x32_bf16 v[46:49], v[226:229], v[188:191], v[46:49]
	v_mfma_f32_16x16x32_bf16 v[50:53], v[218:221], v[200:203], v[50:53]
	v_mfma_f32_16x16x32_bf16 v[38:41], v[226:229], v[200:203], v[38:41]
	v_mfma_f32_16x16x32_bf16 v[42:45], v[218:221], v[208:211], v[42:45]
	v_mfma_f32_16x16x32_bf16 v[34:37], v[226:229], v[208:211], v[34:37]
	v_mfma_f32_16x16x32_bf16 v[62:65], v[222:225], v[184:187], v[62:65]
	v_mfma_f32_16x16x32_bf16 v[54:57], v[230:233], v[184:187], v[54:57]
	v_mfma_f32_16x16x32_bf16 v[58:61], v[222:225], v[192:195], v[58:61]
	v_mfma_f32_16x16x32_bf16 v[46:49], v[230:233], v[192:195], v[46:49]
	v_mfma_f32_16x16x32_bf16 v[50:53], v[222:225], v[204:207], v[50:53]
	v_mfma_f32_16x16x32_bf16 v[38:41], v[230:233], v[204:207], v[38:41]
	v_mfma_f32_16x16x32_bf16 v[42:45], v[222:225], v[212:215], v[42:45]
	v_mfma_f32_16x16x32_bf16 v[34:37], v[230:233], v[212:215], v[34:37]
	s_setprio 0
	s_mov_b32 m0, s94
	v_lshl_add_u64 v[196:197], v[234:235], 0, s[48:49]
	s_barrier
	ds_read_b128 v[180:183], v177 offset:49152
	ds_read_b128 v[184:187], v177 offset:50176
	ds_read_b128 v[188:191], v177 offset:51200
	ds_read_b128 v[192:195], v177 offset:52224
	ds_read_b128 v[200:203], v177 offset:53248
	ds_read_b128 v[204:207], v177 offset:54272
	ds_read_b128 v[208:211], v177 offset:55296
	ds_read_b128 v[212:215], v177 offset:56320
	global_load_lds_dwordx4 v[196:197], off
	v_lshl_add_u64 v[196:197], v[236:237], 0, s[48:49]
	s_mov_b32 m0, s95
	s_nop 0
	global_load_lds_dwordx4 v[196:197], off
	s_barrier
;     DEVI void operator()(AccRef acc, const pg8::Unit& u, int wr, int wc, int fr, int fq) const {
;         const int sel = u.pn >> 2; bf16_t* dst = (bf16_t*)(ws + (size_t)(sel + 1) * UNIT);
;         const int row0 = u.pm * 256 + wr * 64 + fr, col0 = (u.pn & 3) * 256 + wc * 32 + 8 * fq, bcol0 = u.pn * 256 + wc * 32 + 8 * fq + (u.pn >= 12 ? 8 : 0);
; #pragma unroll
;         for (int bj = 0; bj < 2; ++bj)
; #pragma unroll
;             for (int n = 0; n < 2; ++n) { const f32x4 bv = *(const f32x4*)(bias + bcol0 + bj * 128 + n * 4);
; #pragma unroll
;                 for (int ai = 0; ai < 2; ++ai)
; #pragma unroll
;                     for (int m = 0; m < 4; ++m) acc[ai][bj][m][n] += bv; }
	s_waitcnt lgkmcnt(0)
	s_setprio 1
	s_waitcnt lgkmcnt(0)
	v_mfma_f32_16x16x32_bf16 v[94:97], v[142:145], v[180:183], v[94:97]
	v_mfma_f32_16x16x32_bf16 v[86:89], v[150:153], v[180:183], v[86:89]
	v_mfma_f32_16x16x32_bf16 v[90:93], v[142:145], v[188:191], v[90:93]
	v_mfma_f32_16x16x32_bf16 v[78:81], v[150:153], v[188:191], v[78:81]
	v_mfma_f32_16x16x32_bf16 v[82:85], v[142:145], v[200:203], v[82:85]
	v_mfma_f32_16x16x32_bf16 v[70:73], v[150:153], v[200:203], v[70:73]
	v_mfma_f32_16x16x32_bf16 v[74:77], v[142:145], v[208:211], v[74:77]
	v_mfma_f32_16x16x32_bf16 v[66:69], v[150:153], v[208:211], v[66:69]
	v_mfma_f32_16x16x32_bf16 v[94:97], v[146:149], v[184:187], v[94:97]
	v_mfma_f32_16x16x32_bf16 v[86:89], v[154:157], v[184:187], v[86:89]
	v_mfma_f32_16x16x32_bf16 v[90:93], v[146:149], v[192:195], v[90:93]
	v_mfma_f32_16x16x32_bf16 v[78:81], v[154:157], v[192:195], v[78:81]
	v_mfma_f32_16x16x32_bf16 v[82:85], v[146:149], v[204:207], v[82:85]
	v_mfma_f32_16x16x32_bf16 v[70:73], v[154:157], v[204:207], v[70:73]
	v_mfma_f32_16x16x32_bf16 v[74:77], v[146:149], v[212:215], v[74:77]
	v_mfma_f32_16x16x32_bf16 v[66:69], v[154:157], v[212:215], v[66:69]
	s_setprio 0
	s_barrier
	s_add_u32 s8, s86, 0x40080
	s_addc_u32 s9, s87, 0
	s_add_i32 s10, s11, s59
	v_lshl_add_u64 v[142:143], s[8:9], 0, v[132:133]
	s_mov_b32 m0, s10
	s_nop 0
	global_load_lds_dwordx4 v[142:143], off
	v_lshl_add_u64 v[142:143], s[8:9], 0, v[136:137]
	s_add_i32 m0, s10, 0x2000
	s_nop 0
	global_load_lds_dwordx4 v[142:143], off
	s_waitcnt vmcnt(6)
	s_barrier
	s_setprio 1
	v_mfma_f32_16x16x32_bf16 v[30:33], v[218:221], v[180:183], v[30:33]
	v_mfma_f32_16x16x32_bf16 v[22:25], v[226:229], v[180:183], v[22:25]
	v_mfma_f32_16x16x32_bf16 v[26:29], v[218:221], v[188:191], v[26:29]
	v_mfma_f32_16x16x32_bf16 v[14:17], v[226:229], v[188:191], v[14:17]
	v_mfma_f32_16x16x32_bf16 v[18:21], v[218:221], v[200:203], v[18:21]
	v_mfma_f32_16x16x32_bf16 v[6:9], v[226:229], v[200:203], v[6:9]
	v_mfma_f32_16x16x32_bf16 v[10:13], v[218:221], v[208:211], v[10:13]
	v_mfma_f32_16x16x32_bf16 v[2:5], v[226:229], v[208:211], v[2:5]
	v_mfma_f32_16x16x32_bf16 v[30:33], v[222:225], v[184:187], v[30:33]
	v_mfma_f32_16x16x32_bf16 v[22:25], v[230:233], v[184:187], v[22:25]
	v_mfma_f32_16x16x32_bf16 v[26:29], v[222:225], v[192:195], v[26:29]
	v_mfma_f32_16x16x32_bf16 v[14:17], v[230:233], v[192:195], v[14:17]
	v_mfma_f32_16x16x32_bf16 v[18:21], v[222:225], v[204:207], v[18:21]
	v_mfma_f32_16x16x32_bf16 v[6:9], v[230:233], v[204:207], v[6:9]
	v_mfma_f32_16x16x32_bf16 v[10:13], v[222:225], v[212:215], v[10:13]
	v_mfma_f32_16x16x32_bf16 v[2:5], v[230:233], v[212:215], v[2:5]
	s_setprio 0
	s_add_i32 s46, s46, 2
	s_add_u32 vcc_lo, vcc_lo, 0x100
	s_addc_u32 vcc_hi, vcc_hi, 0
	s_add_u32 s84, s84, 0x100
	s_addc_u32 s85, s85, 0
	s_cmp_gt_u32 s46, 13
	s_barrier
	s_cbranch_scc0 .LBB0_409
	s_lshl_b32 s21, s24, 8
	s_cmp_gt_i32 s24, 11
	s_cselect_b32 s8, 8, 0
	v_or_b32_e32 v0, s21, v160
	v_add_u32_e32 v142, s8, v0
	v_ashrrev_i32_e32 v143, 31, v142
	v_lshl_add_u64 v[146:147], v[142:143], 2, s[16:17]
	global_load_dwordx4 v[148:151], v[146:147], off offset:16
	global_load_dwordx4 v[142:145], v[146:147], off
	global_load_dwordx4 v[238:241], v[146:147], off offset:528
	global_load_dwordx4 v[242:245], v[146:147], off offset:512
	s_cmp_gt_i32 s24, 7
	s_waitcnt vmcnt(0)
	v_pk_add_f32 v[128:129], v[128:129], v[144:145]
	v_pk_add_f32 v[126:127], v[126:127], v[142:143]
	v_pk_add_f32 v[124:125], v[124:125], v[144:145]
	v_pk_add_f32 v[122:123], v[122:123], v[142:143]
	v_pk_add_f32 v[116:117], v[116:117], v[144:145]
	v_pk_add_f32 v[114:115], v[114:115], v[142:143]
	v_pk_add_f32 v[108:109], v[108:109], v[144:145]
	v_pk_add_f32 v[106:107], v[106:107], v[142:143]
	v_pk_add_f32 v[96:97], v[96:97], v[144:145]
	v_pk_add_f32 v[94:95], v[94:95], v[142:143]
	v_pk_add_f32 v[92:93], v[92:93], v[144:145]
	v_pk_add_f32 v[90:91], v[90:91], v[142:143]
	v_pk_add_f32 v[84:85], v[84:85], v[144:145]
	v_pk_add_f32 v[82:83], v[82:83], v[142:143]
	v_pk_add_f32 v[76:77], v[76:77], v[144:145]
	v_pk_add_f32 v[74:75], v[74:75], v[142:143]
	v_pk_add_f32 v[142:143], v[120:121], v[150:151]
	v_pk_add_f32 v[144:145], v[118:119], v[148:149]
	v_pk_add_f32 v[118:119], v[112:113], v[150:151]
	v_pk_add_f32 v[120:121], v[110:111], v[148:149]
	v_pk_add_f32 v[110:111], v[104:105], v[150:151]
	v_pk_add_f32 v[112:113], v[102:103], v[148:149]
	v_pk_add_f32 v[102:103], v[100:101], v[150:151]
	v_pk_add_f32 v[104:105], v[98:99], v[148:149]
	v_pk_add_f32 v[98:99], v[88:89], v[150:151]
	v_pk_add_f32 v[100:101], v[86:87], v[148:149]
	v_pk_add_f32 v[86:87], v[80:81], v[150:151]
	v_pk_add_f32 v[88:89], v[78:79], v[148:149]
	v_pk_add_f32 v[78:79], v[72:73], v[150:151]
	v_pk_add_f32 v[80:81], v[70:71], v[148:149]
	v_pk_add_f32 v[70:71], v[68:69], v[150:151]
	v_pk_add_f32 v[72:73], v[66:67], v[148:149]
	v_pk_add_f32 v[154:155], v[56:57], v[240:241]
	v_pk_add_f32 v[150:151], v[64:65], v[244:245]
	v_pk_add_f32 v[152:153], v[62:63], v[242:243]
	v_pk_add_f32 v[62:63], v[60:61], v[244:245]
	v_pk_add_f32 v[64:65], v[58:59], v[242:243]
	v_pk_add_f32 v[58:59], v[52:53], v[244:245]
	v_pk_add_f32 v[60:61], v[50:51], v[242:243]
	v_pk_add_f32 v[50:51], v[44:45], v[244:245]
	v_pk_add_f32 v[52:53], v[42:43], v[242:243]
	v_pk_add_f32 v[42:43], v[32:33], v[244:245]
	v_pk_add_f32 v[44:45], v[30:31], v[242:243]
	v_pk_add_f32 v[30:31], v[28:29], v[244:245]
	v_pk_add_f32 v[32:33], v[26:27], v[242:243]
	v_pk_add_f32 v[26:27], v[20:21], v[244:245]
	v_pk_add_f32 v[28:29], v[18:19], v[242:243]
	v_pk_add_f32 v[18:19], v[12:13], v[244:245]
	v_pk_add_f32 v[20:21], v[10:11], v[242:243]
	v_pk_add_f32 v[156:157], v[54:55], v[238:239]
	v_pk_add_f32 v[146:147], v[48:49], v[240:241]
	v_pk_add_f32 v[148:149], v[46:47], v[238:239]
	v_pk_add_f32 v[54:55], v[40:41], v[240:241]
	v_pk_add_f32 v[56:57], v[38:39], v[238:239]
	v_pk_add_f32 v[46:47], v[36:37], v[240:241]
	v_pk_add_f32 v[48:49], v[34:35], v[238:239]
	v_pk_add_f32 v[38:39], v[24:25], v[240:241]
	v_pk_add_f32 v[40:41], v[22:23], v[238:239]
	v_pk_add_f32 v[34:35], v[16:17], v[240:241]
	v_pk_add_f32 v[36:37], v[14:15], v[238:239]
	v_pk_add_f32 v[22:23], v[8:9], v[240:241]
	v_pk_add_f32 v[24:25], v[6:7], v[238:239]
	v_pk_add_f32 v[14:15], v[4:5], v[240:241]
	v_pk_add_f32 v[16:17], v[2:3], v[238:239]
	s_cbranch_scc1 .LBB0_405
;     DEVI void operator()(AccRef acc, const pg8::Unit& u, int wr, int wc, int fr, int fq) const {
;     ...
;         if (u.pn < 8) {
; #pragma unroll
;             for (int ai = 0; ai < 2; ++ai)
; #pragma unroll
;                 for (int m = 0; m < 4; ++m)
; #pragma unroll
;                     for (int bj = 0; bj < 2; ++bj) { const f32x4 a = acc[ai][bj][m][0], b = acc[ai][bj][m][1];
;                         float s = (a[0] * a[0] + a[1] * a[1]) + (a[2] * a[2] + a[3] * a[3]) + (b[0] * b[0] + b[1] * b[1]) + (b[2] * b[2] + b[3] * b[3]);
;                         s = xrow16_sum(s);
;                         if (fq == 0) Pt[((ai * 128 + wr * 64 + m * 16 + fr) * 2 + bj) * 4 + wc] = s; }
	v_mul_f32_e32 v0, v127, v127
	v_mul_f32_e32 v2, v129, v129
	v_fmac_f32_e32 v0, v126, v126
	v_fmac_f32_e32 v2, v128, v128
	v_add_f32_e32 v0, v0, v2
	v_mul_f32_e32 v2, v145, v145
	v_fmac_f32_e32 v2, v144, v144
	v_add_f32_e32 v0, v0, v2
	v_mul_f32_e32 v2, v143, v143
	v_fmac_f32_e32 v2, v142, v142
	v_add_f32_e32 v0, v2, v0
	v_mov_b32_e32 v2, v0
	s_nop 1
	v_permlane16_swap_b32_e32 v0, v2
	v_add_f32_e32 v0, v0, v2
	v_mov_b32_e32 v2, v0
	s_nop 1
	v_permlane32_swap_b32_e32 v0, v2
	s_and_saveexec_b64 s[60:61], s[4:5]
	v_add_f32_e32 v0, v0, v2
	ds_write_b32 v162, v0
	s_or_b64 exec, exec, s[60:61]
	v_mul_f32_e32 v0, v153, v153
	v_mul_f32_e32 v2, v151, v151
	v_fmac_f32_e32 v0, v152, v152
	v_fmac_f32_e32 v2, v150, v150
	v_add_f32_e32 v0, v0, v2
	v_mul_f32_e32 v2, v157, v157
	v_fmac_f32_e32 v2, v156, v156
	v_add_f32_e32 v0, v2, v0
	v_mul_f32_e32 v2, v155, v155
	v_fmac_f32_e32 v2, v154, v154
	v_add_f32_e32 v0, v2, v0
	v_mov_b32_e32 v2, v0
	s_nop 1
	v_permlane16_swap_b32_e32 v0, v2
	v_add_f32_e32 v0, v0, v2
	v_mov_b32_e32 v2, v0
	s_nop 1
	v_permlane32_swap_b32_e32 v0, v2
	s_and_saveexec_b64 s[60:61], s[4:5]
	v_add_f32_e32 v0, v0, v2
	ds_write_b32 v162, v0 offset:16
	s_or_b64 exec, exec, s[60:61]
	v_mul_f32_e32 v0, v123, v123
	v_mul_f32_e32 v2, v125, v125
	v_fmac_f32_e32 v0, v122, v122
	v_fmac_f32_e32 v2, v124, v124
	v_add_f32_e32 v0, v0, v2
	v_mul_f32_e32 v2, v121, v121
	v_fmac_f32_e32 v2, v120, v120
	v_add_f32_e32 v0, v0, v2
	v_mul_f32_e32 v2, v119, v119
	v_fmac_f32_e32 v2, v118, v118
	v_add_f32_e32 v0, v2, v0
	v_mov_b32_e32 v2, v0
	s_nop 1
	v_permlane16_swap_b32_e32 v0, v2
	v_add_f32_e32 v0, v0, v2
	v_mov_b32_e32 v2, v0
	s_nop 1
	v_permlane32_swap_b32_e32 v0, v2
	s_and_saveexec_b64 s[60:61], s[4:5]
	v_add_f32_e32 v0, v0, v2
	ds_write_b32 v163, v0
	s_or_b64 exec, exec, s[60:61]
	v_mul_f32_e32 v0, v65, v65
	v_mul_f32_e32 v2, v63, v63
	v_fmac_f32_e32 v0, v64, v64
	v_fmac_f32_e32 v2, v62, v62
	v_add_f32_e32 v0, v0, v2
	v_mul_f32_e32 v2, v149, v149
	v_fmac_f32_e32 v2, v148, v148
	v_add_f32_e32 v0, v0, v2
	v_mul_f32_e32 v2, v147, v147
	v_fmac_f32_e32 v2, v146, v146
	v_add_f32_e32 v0, v2, v0
	v_mov_b32_e32 v2, v0
	s_nop 1
	v_permlane16_swap_b32_e32 v0, v2
	v_add_f32_e32 v0, v0, v2
	v_mov_b32_e32 v2, v0
	s_nop 1
	v_permlane32_swap_b32_e32 v0, v2
	s_and_saveexec_b64 s[60:61], s[4:5]
	v_add_f32_e32 v0, v0, v2
	ds_write_b32 v163, v0 offset:16
	s_or_b64 exec, exec, s[60:61]
	v_mul_f32_e32 v0, v115, v115
	v_mul_f32_e32 v2, v117, v117
	v_fmac_f32_e32 v0, v114, v114
	v_fmac_f32_e32 v2, v116, v116
	v_add_f32_e32 v0, v0, v2
	v_mul_f32_e32 v2, v113, v113
	v_fmac_f32_e32 v2, v112, v112
	v_add_f32_e32 v0, v0, v2
	v_mul_f32_e32 v2, v111, v111
	v_fmac_f32_e32 v2, v110, v110
	v_add_f32_e32 v0, v2, v0
	v_mov_b32_e32 v2, v0
	s_nop 1
	v_permlane16_swap_b32_e32 v0, v2
	v_add_f32_e32 v0, v0, v2
	v_mov_b32_e32 v2, v0
	s_nop 1
	v_permlane32_swap_b32_e32 v0, v2
	s_and_saveexec_b64 s[60:61], s[4:5]
	v_add_f32_e32 v0, v0, v2
	ds_write_b32 v164, v0
	s_or_b64 exec, exec, s[60:61]
	v_mul_f32_e32 v0, v61, v61
	v_mul_f32_e32 v2, v59, v59
	v_fmac_f32_e32 v0, v60, v60
	v_fmac_f32_e32 v2, v58, v58
	v_add_f32_e32 v0, v0, v2
	v_mul_f32_e32 v2, v57, v57
	v_fmac_f32_e32 v2, v56, v56
	v_add_f32_e32 v0, v0, v2
	v_mul_f32_e32 v2, v55, v55
	v_fmac_f32_e32 v2, v54, v54
	v_add_f32_e32 v0, v2, v0
	v_mov_b32_e32 v2, v0
	s_nop 1
	v_permlane16_swap_b32_e32 v0, v2
	v_add_f32_e32 v0, v0, v2
	v_mov_b32_e32 v2, v0
	s_nop 1
	v_permlane32_swap_b32_e32 v0, v2
	s_and_saveexec_b64 s[60:61], s[4:5]
	v_add_f32_e32 v0, v0, v2
	ds_write_b32 v164, v0 offset:16
	s_or_b64 exec, exec, s[60:61]
	v_mul_f32_e32 v0, v107, v107
	v_mul_f32_e32 v2, v109, v109
	v_fmac_f32_e32 v0, v106, v106
	v_fmac_f32_e32 v2, v108, v108
	v_add_f32_e32 v0, v0, v2
	v_mul_f32_e32 v2, v105, v105
	v_fmac_f32_e32 v2, v104, v104
	v_add_f32_e32 v0, v0, v2
	v_mul_f32_e32 v2, v103, v103
	v_fmac_f32_e32 v2, v102, v102
	v_add_f32_e32 v0, v2, v0
	v_mov_b32_e32 v2, v0
	s_nop 1
	v_permlane16_swap_b32_e32 v0, v2
	v_add_f32_e32 v0, v0, v2
	v_mov_b32_e32 v2, v0
	s_nop 1
	v_permlane32_swap_b32_e32 v0, v2
	s_and_saveexec_b64 s[60:61], s[4:5]
	v_add_f32_e32 v0, v0, v2
	ds_write_b32 v165, v0
	s_or_b64 exec, exec, s[60:61]
	v_mul_f32_e32 v0, v53, v53
	v_mul_f32_e32 v2, v51, v51
	v_fmac_f32_e32 v0, v52, v52
	v_fmac_f32_e32 v2, v50, v50
	v_add_f32_e32 v0, v0, v2
	v_mul_f32_e32 v2, v49, v49
	v_fmac_f32_e32 v2, v48, v48
	v_add_f32_e32 v0, v0, v2
	v_mul_f32_e32 v2, v47, v47
	v_fmac_f32_e32 v2, v46, v46
	v_add_f32_e32 v0, v2, v0
	v_mov_b32_e32 v2, v0
	s_nop 1
	v_permlane16_swap_b32_e32 v0, v2
	v_add_f32_e32 v0, v0, v2
	v_mov_b32_e32 v2, v0
	s_nop 1
	v_permlane32_swap_b32_e32 v0, v2
	s_and_saveexec_b64 s[60:61], s[4:5]
	v_add_f32_e32 v0, v0, v2
	ds_write_b32 v165, v0 offset:16
;     DEVI void operator()(AccRef acc, const pg8::Unit& u, int wr, int wc, int fr, int fq) const {
;     ...
;         if (u.pn < 8) {
; #pragma unroll
;             for (int ai = 0; ai < 2; ++ai)
; #pragma unroll
;                 for (int m = 0; m < 4; ++m)
; #pragma unroll
;                     for (int bj = 0; bj < 2; ++bj) { const f32x4 a = acc[ai][bj][m][0], b = acc[ai][bj][m][1];
;                         float s = (a[0] * a[0] + a[1] * a[1]) + (a[2] * a[2] + a[3] * a[3]) + (b[0] * b[0] + b[1] * b[1]) + (b[2] * b[2] + b[3] * b[3]);
;                         s = xrow16_sum(s);
;                         if (fq == 0) Pt[((ai * 128 + wr * 64 + m * 16 + fr) * 2 + bj) * 4 + wc] = s; }
	s_or_b64 exec, exec, s[60:61]
	v_mul_f32_e32 v0, v95, v95
	v_mul_f32_e32 v2, v97, v97
	v_fmac_f32_e32 v0, v94, v94
	v_fmac_f32_e32 v2, v96, v96
	v_add_f32_e32 v0, v0, v2
	v_mul_f32_e32 v2, v101, v101
	v_fmac_f32_e32 v2, v100, v100
	v_add_f32_e32 v0, v0, v2
	v_mul_f32_e32 v2, v99, v99
	v_fmac_f32_e32 v2, v98, v98
	v_add_f32_e32 v0, v2, v0
	v_mov_b32_e32 v2, v0
	s_nop 1
	v_permlane16_swap_b32_e32 v0, v2
	v_add_f32_e32 v0, v0, v2
	v_mov_b32_e32 v2, v0
	s_nop 1
	v_permlane32_swap_b32_e32 v0, v2
	s_and_saveexec_b64 s[60:61], s[4:5]
	v_add_f32_e32 v0, v0, v2
	ds_write_b32 v166, v0
	s_or_b64 exec, exec, s[60:61]
	v_mul_f32_e32 v0, v45, v45
	v_mul_f32_e32 v2, v43, v43
	v_fmac_f32_e32 v0, v44, v44
	v_fmac_f32_e32 v2, v42, v42
	v_add_f32_e32 v0, v0, v2
	v_mul_f32_e32 v2, v41, v41
	v_fmac_f32_e32 v2, v40, v40
	v_add_f32_e32 v0, v0, v2
	v_mul_f32_e32 v2, v39, v39
	v_fmac_f32_e32 v2, v38, v38
	v_add_f32_e32 v0, v2, v0
	v_mov_b32_e32 v2, v0
	s_nop 1
	v_permlane16_swap_b32_e32 v0, v2
	v_add_f32_e32 v0, v0, v2
	v_mov_b32_e32 v2, v0
	s_nop 1
	v_permlane32_swap_b32_e32 v0, v2
	s_and_saveexec_b64 s[60:61], s[4:5]
	v_add_f32_e32 v0, v0, v2
	ds_write_b32 v166, v0 offset:16
	s_or_b64 exec, exec, s[60:61]
	v_mul_f32_e32 v0, v91, v91
	v_mul_f32_e32 v2, v93, v93
	v_fmac_f32_e32 v0, v90, v90
	v_fmac_f32_e32 v2, v92, v92
	v_add_f32_e32 v0, v0, v2
	v_mul_f32_e32 v2, v89, v89
	v_fmac_f32_e32 v2, v88, v88
	v_add_f32_e32 v0, v0, v2
	v_mul_f32_e32 v2, v87, v87
	v_fmac_f32_e32 v2, v86, v86
	v_add_f32_e32 v0, v2, v0
	v_mov_b32_e32 v2, v0
	s_nop 1
	v_permlane16_swap_b32_e32 v0, v2
	v_add_f32_e32 v0, v0, v2
	v_mov_b32_e32 v2, v0
	s_nop 1
	v_permlane32_swap_b32_e32 v0, v2
	s_and_saveexec_b64 s[60:61], s[4:5]
	v_add_f32_e32 v0, v0, v2
	ds_write_b32 v167, v0
	s_or_b64 exec, exec, s[60:61]
	v_mul_f32_e32 v0, v33, v33
	v_mul_f32_e32 v2, v31, v31
	v_fmac_f32_e32 v0, v32, v32
	v_fmac_f32_e32 v2, v30, v30
	v_add_f32_e32 v0, v0, v2
	v_mul_f32_e32 v2, v37, v37
	v_fmac_f32_e32 v2, v36, v36
	v_add_f32_e32 v0, v0, v2
	v_mul_f32_e32 v2, v35, v35
	v_fmac_f32_e32 v2, v34, v34
	v_add_f32_e32 v0, v2, v0
	v_mov_b32_e32 v2, v0
	s_nop 1
	v_permlane16_swap_b32_e32 v0, v2
	v_add_f32_e32 v0, v0, v2
	v_mov_b32_e32 v2, v0
	s_nop 1
	v_permlane32_swap_b32_e32 v0, v2
	s_and_saveexec_b64 s[60:61], s[4:5]
	v_add_f32_e32 v0, v0, v2
	ds_write_b32 v167, v0 offset:16
	s_or_b64 exec, exec, s[60:61]
	v_mul_f32_e32 v0, v83, v83
	v_mul_f32_e32 v2, v85, v85
	v_fmac_f32_e32 v0, v82, v82
	v_fmac_f32_e32 v2, v84, v84
	v_add_f32_e32 v0, v0, v2
	v_mul_f32_e32 v2, v81, v81
	v_fmac_f32_e32 v2, v80, v80
	v_add_f32_e32 v0, v0, v2
	v_mul_f32_e32 v2, v79, v79
	v_fmac_f32_e32 v2, v78, v78
	v_add_f32_e32 v0, v2, v0
	v_mov_b32_e32 v2, v0
	s_nop 1
	v_permlane16_swap_b32_e32 v0, v2
	v_add_f32_e32 v0, v0, v2
	v_mov_b32_e32 v2, v0
	s_nop 1
	v_permlane32_swap_b32_e32 v0, v2
	s_and_saveexec_b64 s[60:61], s[4:5]
	v_add_f32_e32 v0, v0, v2
	ds_write_b32 v168, v0
	s_or_b64 exec, exec, s[60:61]
	v_mul_f32_e32 v0, v29, v29
	v_mul_f32_e32 v2, v27, v27
	v_fmac_f32_e32 v0, v28, v28
	v_fmac_f32_e32 v2, v26, v26
	v_add_f32_e32 v0, v0, v2
	v_mul_f32_e32 v2, v25, v25
	v_fmac_f32_e32 v2, v24, v24
	v_add_f32_e32 v0, v0, v2
	v_mul_f32_e32 v2, v23, v23
	v_fmac_f32_e32 v2, v22, v22
	v_add_f32_e32 v0, v2, v0
	v_mov_b32_e32 v2, v0
	s_nop 1
	v_permlane16_swap_b32_e32 v0, v2
	v_add_f32_e32 v0, v0, v2
	v_mov_b32_e32 v2, v0
	s_nop 1
	v_permlane32_swap_b32_e32 v0, v2
	s_and_saveexec_b64 s[60:61], s[4:5]
	v_add_f32_e32 v0, v0, v2
	ds_write_b32 v168, v0 offset:16
	s_or_b64 exec, exec, s[60:61]
	v_mul_f32_e32 v0, v75, v75
	v_mul_f32_e32 v2, v77, v77
	v_fmac_f32_e32 v0, v74, v74
	v_fmac_f32_e32 v2, v76, v76
	v_add_f32_e32 v0, v0, v2
	v_mul_f32_e32 v2, v73, v73
	v_fmac_f32_e32 v2, v72, v72
	v_add_f32_e32 v0, v0, v2
	v_mul_f32_e32 v2, v71, v71
	v_fmac_f32_e32 v2, v70, v70
	v_add_f32_e32 v0, v2, v0
	v_mov_b32_e32 v2, v0
	s_nop 1
	v_permlane16_swap_b32_e32 v0, v2
	v_add_f32_e32 v0, v0, v2
	v_mov_b32_e32 v2, v0
	s_nop 1
	v_permlane32_swap_b32_e32 v0, v2
	s_and_saveexec_b64 s[60:61], s[4:5]
	v_add_f32_e32 v0, v0, v2
	ds_write_b32 v169, v0
	s_or_b64 exec, exec, s[60:61]
	v_mul_f32_e32 v0, v21, v21
	v_mul_f32_e32 v2, v19, v19
	v_fmac_f32_e32 v0, v20, v20
	v_fmac_f32_e32 v2, v18, v18
	v_add_f32_e32 v0, v0, v2
	v_mul_f32_e32 v2, v17, v17
	v_fmac_f32_e32 v2, v16, v16
	v_add_f32_e32 v0, v0, v2
	v_mul_f32_e32 v2, v15, v15
	v_fmac_f32_e32 v2, v14, v14
	v_add_f32_e32 v0, v2, v0
	v_mov_b32_e32 v2, v0
	s_nop 1
	v_permlane16_swap_b32_e32 v0, v2
	v_add_f32_e32 v0, v0, v2
	v_mov_b32_e32 v2, v0
	s_nop 1
	v_permlane32_swap_b32_e32 v0, v2
	s_and_saveexec_b64 s[60:61], s[4:5]
	s_cbranch_execz .LBB0_404
	v_add_f32_e32 v0, v0, v2
	ds_write_b32 v169, v0 offset:16
	s_branch .LBB0_404
